# plus: the four gate pieces of the first down-GEMM epilogue requested together (one wait instead of three)
# baseline (speedup 1.0000x reference)
;     __device__ __forceinline__ void operator()(const f32x4 (&acc)[2][2][4][2], const Unit& u, int wr, int wc, int fr, int fq) const {
;     ...
;         const int r = u.pm >> 3;
;         const float* src = src_lat;
;         f32x4 gv[2][2];
; #pragma unroll
;         for (int bj = 0; bj < 2; ++bj)
; #pragma unroll
;             for (int n = 0; n < 2; ++n) {
;                 f32x4 g = *(const f32x4*)(gate + (size_t)r * NMODC + col0 + bj * HALF + n * 16) * coef;
;                 if (cscale) g = g * *(const f32x4*)(cscale + col0 + bj * HALF + n * 16);
;                 gv[bj][n] = g;
;             }
; #pragma unroll
;         for (int ai = 0; ai < 2; ++ai)
; #pragma unroll
;             for (int m = 0; m < 4; ++m) {
;                 const size_t ro = (size_t)(row0 + ai * HALF + m * 16) * DM + col0;
; #pragma unroll
;                 for (int bj = 0; bj < 2; ++bj)
; #pragma unroll
;                     for (int n = 0; n < 2; ++n) {
;                         const f32x4 s = *(const f32x4*)(src + ro + bj * HALF + n * 16);
;                         *(f32x4*)(dst + ro + bj * HALF + n * 16) = s + acc[ai][bj][m][n] * gv[bj][n];
;                     }
.LBB0_265:
	v_or_b32_e32 v140, s91, v184
	v_lshl_add_u32 v142, s17, 8, v178
	v_lshl_or_b32 v140, s16, 8, v140
	s_mov_b64 s[44:45], -1
	s_cmp_lt_i32 s17, 32
	v_ashrrev_i32_e32 v141, 31, v140
	v_ashrrev_i32_e32 v143, 31, v142
	s_mov_b32 s96, s65
	s_mov_b32 s97, s52
	s_cbranch_scc0 .LBB0_267
	s_ashr_i32 s1, s17, 3
	s_mul_hi_i32 s21, s1, 0x12000
	s_mul_i32 s1, s1, 0x12000
	s_add_u32 s28, s28, s1
	s_addc_u32 s29, s29, s21
	v_lshl_add_u64 v[160:161], v[140:141], 2, s[28:29]
	global_load_dwordx4 v[144:147], v[160:161], off
	global_load_dwordx4 v[188:191], v[160:161], off offset:576
	global_load_dwordx4 v[196:199], v[160:161], off offset:64
	global_load_dwordx4 v[200:203], v[160:161], off offset:512
	s_mov_b64 s[44:45], 0
	v_lshlrev_b64 v[160:161], 11, v[142:143]
	v_lshl_add_u64 v[160:161], v[160:161], 0, v[140:141]
	v_lshlrev_b64 v[160:161], 2, v[160:161]
	s_waitcnt vmcnt(0)
	v_pk_mul_f32 v[156:157], v[146:147], s[0:1] op_sel_hi:[1,0]
	v_pk_mul_f32 v[158:159], v[144:145], s[0:1] op_sel_hi:[1,0]
	v_pk_mul_f32 v[152:153], s[0:1], v[198:199] op_sel_hi:[0,1]
	v_pk_mul_f32 v[154:155], s[0:1], v[196:197] op_sel_hi:[0,1]
	v_pk_mul_f32 v[148:149], s[0:1], v[202:203] op_sel_hi:[0,1]
	v_pk_mul_f32 v[150:151], s[0:1], v[200:201] op_sel_hi:[0,1]
	v_pk_mul_f32 v[144:145], s[0:1], v[190:191] op_sel_hi:[0,1]
	v_pk_mul_f32 v[146:147], s[0:1], v[188:189] op_sel_hi:[0,1]
	s_waitcnt lgkmcnt(0)
	v_add_u32_e32 v224, 0x20000, v160
	v_add_u32_e32 v225, 0x40000, v160
	v_add_u32_e32 v226, 0x60000, v160
	v_add_u32_e32 v227, 0x100000, v160
	v_add_u32_e32 v228, 0x120000, v160
	v_add_u32_e32 v229, 0x140000, v160
	v_add_u32_e32 v230, 0x160000, v160
	global_load_dwordx4 v[188:191], v160, s[26:27]
	global_load_dwordx4 v[192:195], v160, s[26:27] offset:64
	global_load_dwordx4 v[196:199], v160, s[26:27] offset:512
	global_load_dwordx4 v[200:203], v160, s[26:27] offset:576
	global_load_dwordx4 v[236:239], v224, s[26:27]
	global_load_dwordx4 v[240:243], v224, s[26:27] offset:64
	global_load_dwordx4 v[232:235], v224, s[26:27] offset:512
	global_load_dwordx4 v[248:251], v224, s[26:27] offset:576
	s_waitcnt vmcnt(4)
	v_pk_fma_f32 v[190:191], v[128:129], v[156:157], v[190:191]
	v_pk_fma_f32 v[188:189], v[126:127], v[158:159], v[188:189]
	v_pk_fma_f32 v[194:195], v[124:125], v[152:153], v[194:195]
	v_pk_fma_f32 v[192:193], v[122:123], v[154:155], v[192:193]
	v_pk_fma_f32 v[198:199], v[88:89], v[148:149], v[198:199]
	v_pk_fma_f32 v[196:197], v[86:87], v[150:151], v[196:197]
	v_pk_fma_f32 v[202:203], v[44:45], v[144:145], v[202:203]
	v_pk_fma_f32 v[200:201], v[42:43], v[146:147], v[200:201]
	global_store_dwordx4 v160, v[188:191], s[38:39]
	global_store_dwordx4 v160, v[192:195], s[38:39] offset:64
	global_store_dwordx4 v160, v[196:199], s[38:39] offset:512
	global_store_dwordx4 v160, v[200:203], s[38:39] offset:576
	global_load_dwordx4 v[188:191], v225, s[26:27]
	global_load_dwordx4 v[192:195], v225, s[26:27] offset:64
	global_load_dwordx4 v[196:199], v225, s[26:27] offset:512
	global_load_dwordx4 v[200:203], v225, s[26:27] offset:576
	s_waitcnt vmcnt(8)
	v_pk_fma_f32 v[238:239], v[120:121], v[156:157], v[238:239]
	v_pk_fma_f32 v[236:237], v[118:119], v[158:159], v[236:237]
	v_pk_fma_f32 v[242:243], v[116:117], v[152:153], v[242:243]
	v_pk_fma_f32 v[240:241], v[114:115], v[154:155], v[240:241]
	v_pk_fma_f32 v[234:235], v[104:105], v[148:149], v[234:235]
	v_pk_fma_f32 v[232:233], v[102:103], v[150:151], v[232:233]
	v_pk_fma_f32 v[250:251], v[64:65], v[144:145], v[250:251]
	v_pk_fma_f32 v[248:249], v[62:63], v[146:147], v[248:249]
	global_store_dwordx4 v224, v[236:239], s[38:39]
	global_store_dwordx4 v224, v[240:243], s[38:39] offset:64
	global_store_dwordx4 v224, v[232:235], s[38:39] offset:512
	global_store_dwordx4 v224, v[248:251], s[38:39] offset:576
	global_load_dwordx4 v[236:239], v226, s[26:27]
	global_load_dwordx4 v[240:243], v226, s[26:27] offset:64
	global_load_dwordx4 v[232:235], v226, s[26:27] offset:512
	global_load_dwordx4 v[248:251], v226, s[26:27] offset:576
	s_waitcnt vmcnt(8)
	v_pk_fma_f32 v[190:191], v[112:113], v[156:157], v[190:191]
	v_pk_fma_f32 v[188:189], v[110:111], v[158:159], v[188:189]
	v_pk_fma_f32 v[194:195], v[108:109], v[152:153], v[194:195]
	v_pk_fma_f32 v[192:193], v[106:107], v[154:155], v[192:193]
	v_pk_fma_f32 v[198:199], v[100:101], v[148:149], v[198:199]
	v_pk_fma_f32 v[196:197], v[98:99], v[150:151], v[196:197]
	v_pk_fma_f32 v[202:203], v[76:77], v[144:145], v[202:203]
	v_pk_fma_f32 v[200:201], v[74:75], v[146:147], v[200:201]
	global_store_dwordx4 v225, v[188:191], s[38:39]
	global_store_dwordx4 v225, v[192:195], s[38:39] offset:64
	global_store_dwordx4 v225, v[196:199], s[38:39] offset:512
	global_store_dwordx4 v225, v[200:203], s[38:39] offset:576
	global_load_dwordx4 v[188:191], v227, s[26:27]
	global_load_dwordx4 v[192:195], v227, s[26:27] offset:64
	global_load_dwordx4 v[196:199], v227, s[26:27] offset:512
	global_load_dwordx4 v[200:203], v227, s[26:27] offset:576
	s_waitcnt vmcnt(8)
;     __device__ __forceinline__ void operator()(const f32x4 (&acc)[2][2][4][2], const Unit& u, int wr, int wc, int fr, int fq) const {
;     ...
;         for (int ai = 0; ai < 2; ++ai)
; #pragma unroll
;             for (int m = 0; m < 4; ++m) {
;                 const size_t ro = (size_t)(row0 + ai * HALF + m * 16) * DM + col0;
; #pragma unroll
;                 for (int bj = 0; bj < 2; ++bj)
; #pragma unroll
;                     for (int n = 0; n < 2; ++n) {
;                         const f32x4 s = *(const f32x4*)(src + ro + bj * HALF + n * 16);
;                         *(f32x4*)(dst + ro + bj * HALF + n * 16) = s + acc[ai][bj][m][n] * gv[bj][n];
;                     }
	v_pk_fma_f32 v[238:239], v[96:97], v[156:157], v[238:239]
	v_pk_fma_f32 v[236:237], v[94:95], v[158:159], v[236:237]
	v_pk_fma_f32 v[242:243], v[92:93], v[152:153], v[242:243]
	v_pk_fma_f32 v[240:241], v[90:91], v[154:155], v[240:241]
	v_pk_fma_f32 v[234:235], v[84:85], v[148:149], v[234:235]
	v_pk_fma_f32 v[232:233], v[82:83], v[150:151], v[232:233]
	v_pk_fma_f32 v[250:251], v[80:81], v[144:145], v[250:251]
	v_pk_fma_f32 v[248:249], v[78:79], v[146:147], v[248:249]
	global_store_dwordx4 v226, v[236:239], s[38:39]
	global_store_dwordx4 v226, v[240:243], s[38:39] offset:64
	global_store_dwordx4 v226, v[232:235], s[38:39] offset:512
	global_store_dwordx4 v226, v[248:251], s[38:39] offset:576
	global_load_dwordx4 v[236:239], v228, s[26:27]
	global_load_dwordx4 v[240:243], v228, s[26:27] offset:64
	global_load_dwordx4 v[232:235], v228, s[26:27] offset:512
	global_load_dwordx4 v[248:251], v228, s[26:27] offset:576
	s_waitcnt vmcnt(8)
	v_pk_fma_f32 v[190:191], v[72:73], v[156:157], v[190:191]
	v_pk_fma_f32 v[188:189], v[70:71], v[158:159], v[188:189]
	v_pk_fma_f32 v[194:195], v[68:69], v[152:153], v[194:195]
	v_pk_fma_f32 v[192:193], v[66:67], v[154:155], v[192:193]
	v_pk_fma_f32 v[198:199], v[60:61], v[148:149], v[198:199]
	v_pk_fma_f32 v[196:197], v[58:59], v[150:151], v[196:197]
	v_pk_fma_f32 v[202:203], v[56:57], v[144:145], v[202:203]
	v_pk_fma_f32 v[200:201], v[54:55], v[146:147], v[200:201]
	global_store_dwordx4 v227, v[188:191], s[38:39]
	global_store_dwordx4 v227, v[192:195], s[38:39] offset:64
	global_store_dwordx4 v227, v[196:199], s[38:39] offset:512
	global_store_dwordx4 v227, v[200:203], s[38:39] offset:576
	global_load_dwordx4 v[188:191], v229, s[26:27]
	global_load_dwordx4 v[192:195], v229, s[26:27] offset:64
	global_load_dwordx4 v[196:199], v229, s[26:27] offset:512
	global_load_dwordx4 v[200:203], v229, s[26:27] offset:576
	s_waitcnt vmcnt(8)
	v_pk_fma_f32 v[238:239], v[52:53], v[156:157], v[238:239]
	v_pk_fma_f32 v[236:237], v[50:51], v[158:159], v[236:237]
	v_pk_fma_f32 v[242:243], v[48:49], v[152:153], v[242:243]
	v_pk_fma_f32 v[240:241], v[46:47], v[154:155], v[240:241]
	v_pk_fma_f32 v[234:235], v[40:41], v[148:149], v[234:235]
	v_pk_fma_f32 v[232:233], v[38:39], v[150:151], v[232:233]
	v_pk_fma_f32 v[250:251], v[36:37], v[144:145], v[250:251]
	v_pk_fma_f32 v[248:249], v[34:35], v[146:147], v[248:249]
	global_store_dwordx4 v228, v[236:239], s[38:39]
	global_store_dwordx4 v228, v[240:243], s[38:39] offset:64
	global_store_dwordx4 v228, v[232:235], s[38:39] offset:512
	global_store_dwordx4 v228, v[248:251], s[38:39] offset:576
	global_load_dwordx4 v[236:239], v230, s[26:27]
	global_load_dwordx4 v[240:243], v230, s[26:27] offset:64
	global_load_dwordx4 v[232:235], v230, s[26:27] offset:512
	global_load_dwordx4 v[248:251], v230, s[26:27] offset:576
	s_waitcnt vmcnt(8)
	v_pk_fma_f32 v[190:191], v[32:33], v[156:157], v[190:191]
	v_pk_fma_f32 v[188:189], v[30:31], v[158:159], v[188:189]
	v_pk_fma_f32 v[194:195], v[28:29], v[152:153], v[194:195]
	v_pk_fma_f32 v[192:193], v[26:27], v[154:155], v[192:193]
	v_pk_fma_f32 v[198:199], v[24:25], v[148:149], v[198:199]
	v_pk_fma_f32 v[196:197], v[22:23], v[150:151], v[196:197]
	v_pk_fma_f32 v[202:203], v[20:21], v[144:145], v[202:203]
	v_pk_fma_f32 v[200:201], v[18:19], v[146:147], v[200:201]
	global_store_dwordx4 v229, v[188:191], s[38:39]
	global_store_dwordx4 v229, v[192:195], s[38:39] offset:64
	global_store_dwordx4 v229, v[196:199], s[38:39] offset:512
	global_store_dwordx4 v229, v[200:203], s[38:39] offset:576
	s_waitcnt vmcnt(4)
	v_pk_fma_f32 v[238:239], v[16:17], v[156:157], v[238:239]
	v_pk_fma_f32 v[236:237], v[14:15], v[158:159], v[236:237]
	v_pk_fma_f32 v[242:243], v[12:13], v[152:153], v[242:243]
	v_pk_fma_f32 v[240:241], v[10:11], v[154:155], v[240:241]
	v_pk_fma_f32 v[234:235], v[8:9], v[148:149], v[234:235]
	v_pk_fma_f32 v[232:233], v[6:7], v[150:151], v[232:233]
	v_pk_fma_f32 v[250:251], v[4:5], v[144:145], v[250:251]
	v_pk_fma_f32 v[248:249], v[2:3], v[146:147], v[248:249]
	global_store_dwordx4 v230, v[236:239], s[38:39]
	global_store_dwordx4 v230, v[240:243], s[38:39] offset:64
	global_store_dwordx4 v230, v[232:235], s[38:39] offset:512
	global_store_dwordx4 v230, v[248:251], s[38:39] offset:576
